# mix-in q/k epilogue: rope cos/sin table kept in LDS (static LDS +8 KiB, filled per phase), ds_read instead of 4 global loads per row block; row-block waits no longer block on the previous stores
# baseline (speedup 1.0000x reference)
.LBB0_404:
	s_andn2_b64 vcc, exec, s[2:3]
	s_mov_b64 s[12:13], 0
	s_mov_b64 s[64:65], 0x39e0080
	s_mov_b64 s[68:69], 0x3a00080
	s_cbranch_vccnz .LBB0_495
	s_cmp_gt_i32 s59, 0
	s_mov_b64 s[12:13], -1
	s_cbranch_scc0 .LBB0_495
	s_cmp_gt_i32 s59, 1
	s_mov_b64 s[20:21], -1
	s_cbranch_scc0 .LBB0_494
	v_readlane_b32 s2, v254, 61
	v_readlane_b32 s3, v254, 62
	s_andn2_b64 vcc, exec, s[2:3]
	s_cbranch_vccnz .LBB0_493
	s_add_u32 s28, s14, 0x1080000
	s_mul_i32 s2, s77, 5
	s_addc_u32 s29, s15, 0
	s_ashr_i32 s3, s2, 31
	s_lshl_b64 s[2:3], s[2:3], 20
	s_add_u32 s30, s2, 0x100000
	s_addc_u32 s31, s3, 0
	s_add_u32 s34, s2, 0x400000
	s_addc_u32 s35, s3, 0
	s_lshl_b32 s8, s77, 6
	s_ashr_i32 s9, s8, 31
	s_mov_b32 s56, -1
	v_readlane_b32 s36, v255, 18
	s_mov_b32 s57, s79
	v_lshlrev_b32_e32 v0, 4, v190
	s_add_u32 s98, s74, 0x122e0000
	s_addc_u32 s99, s75, 0
	global_load_dwordx4 v[4:7], v0, s[98:99]
	v_add_u32_e32 v0, 0x21040, v0
	s_waitcnt vmcnt(0)
	ds_write_b128 v0, v[4:7]
	s_waitcnt lgkmcnt(0)
	s_branch .LBB0_411
.LBB0_409:
	s_or_b64 exec, exec, s[2:3]
	s_waitcnt lgkmcnt(0)
	v_add_f32_e32 v10, v10, v11
	v_fmamk_f32 v10, v10, 0x3c800000, v192
	v_mul_f32_e32 v11, 0x4b800000, v10
	v_cmp_gt_f32_e32 vcc, s58, v10
	v_lshl_add_u64 v[0:1], v[0:1], 0, v[144:145]
	s_nop 0
	v_cndmask_b32_e32 v10, v10, v11, vcc
	v_rsq_f32_e32 v10, v10
	s_nop 0
	v_mul_f32_e32 v11, 0x45800000, v10
	v_cndmask_b32_e32 v10, v10, v11, vcc
	v_pk_mul_f32 v[34:35], v[34:35], v[10:11] op_sel_hi:[1,0]
	v_pk_mul_f32 v[12:13], v[38:39], v[10:11] op_sel_hi:[1,0]
	v_pk_mul_f32 v[32:33], v[36:37], v[10:11] op_sel_hi:[1,0]
	v_pk_mul_f32 v[34:35], v[138:139], v[34:35]
	v_pk_mul_f32 v[14:15], v[40:41], v[10:11] op_sel_hi:[1,0]
	v_pk_mul_f32 v[12:13], v[142:143], v[12:13]
	v_pk_mul_f32 v[32:33], v[136:137], v[32:33]
	v_pk_mul_f32 v[2:3], v[2:3], v[10:11] op_sel_hi:[1,0]
	s_waitcnt lgkmcnt(0)
	v_pk_mul_f32 v[36:37], v[30:31], v[34:35]
	v_pk_mul_f32 v[14:15], v[140:141], v[14:15]
	v_pk_mul_f32 v[6:7], v[6:7], v[10:11] op_sel_hi:[1,0]
	v_pk_mul_f32 v[8:9], v[8:9], v[10:11] op_sel_hi:[1,0]
	v_pk_mul_f32 v[4:5], v[4:5], v[10:11] op_sel_hi:[1,0]
	v_pk_mul_f32 v[2:3], v[130:131], v[2:3]
	v_pk_mul_f32 v[10:11], v[28:29], v[32:33]
	v_pk_fma_f32 v[36:37], v[22:23], v[12:13], v[36:37] neg_lo:[0,0,1] neg_hi:[0,0,1]
	v_pk_mul_f32 v[12:13], v[30:31], v[12:13]
	v_pk_mul_f32 v[6:7], v[134:135], v[6:7]
	v_pk_mul_f32 v[4:5], v[128:129], v[4:5]
	v_pk_fma_f32 v[10:11], v[20:21], v[14:15], v[10:11] neg_lo:[0,0,1] neg_hi:[0,0,1]
	v_pk_mul_f32 v[14:15], v[28:29], v[14:15]
	v_pk_fma_f32 v[12:13], v[22:23], v[34:35], v[12:13]
	v_pk_mul_f32 v[22:23], v[26:27], v[2:3]
	v_pk_mul_f32 v[8:9], v[132:133], v[8:9]
	v_pk_fma_f32 v[14:15], v[20:21], v[32:33], v[14:15]
	v_pk_mul_f32 v[20:21], v[24:25], v[4:5]
	v_pk_fma_f32 v[22:23], v[18:19], v[6:7], v[22:23] neg_lo:[0,0,1] neg_hi:[0,0,1]
	v_pk_mul_f32 v[6:7], v[26:27], v[6:7]
	v_pk_fma_f32 v[20:21], v[16:17], v[8:9], v[20:21] neg_lo:[0,0,1] neg_hi:[0,0,1]
	v_pk_mul_f32 v[8:9], v[24:25], v[8:9]
	v_pk_fma_f32 v[2:3], v[18:19], v[2:3], v[6:7]
	v_cvt_pk_bf16_f32 v6, v10, v11
	v_cvt_pk_bf16_f32 v7, v36, v37
	v_pk_fma_f32 v[4:5], v[16:17], v[4:5], v[8:9]
	global_store_dwordx2 v[0:1], v[6:7], off
	v_cvt_pk_bf16_f32 v6, v14, v15
	v_cvt_pk_bf16_f32 v7, v12, v13
	global_store_dwordx2 v[0:1], v[6:7], off offset:32
	v_cvt_pk_bf16_f32 v6, v20, v21
	v_cvt_pk_bf16_f32 v7, v22, v23
	global_store_dwordx2 v[0:1], v[6:7], off offset:64
	v_cvt_pk_bf16_f32 v4, v4, v5
	v_cvt_pk_bf16_f32 v5, v2, v3
	global_store_dwordx2 v[0:1], v[4:5], off offset:96

.LBB0_461:
	s_or_b64 exec, exec, s[2:3]
	s_add_u32 s98, s74, 0x122e0000
	s_sub_u32 s98, 0x21040, s98
	v_or_b32_e32 v146, s26, v159
	v_lshl_add_u32 v158, v160, 7, v146
	v_lshlrev_b32_e32 v146, 2, v159
	v_lshl_or_b32 v146, v160, 9, v146
	v_and_b32_e32 v147, 64, v194
	v_add_u32_e32 v218, 0x20800, v146
	v_xor_b32_e32 v146, 16, v194
	v_add_u32_e32 v147, 64, v147
	v_cmp_lt_i32_e64 s[6:7], v146, v147
	v_lshl_add_u64 v[128:129], s[8:9], 2, v[128:129]
	v_lshlrev_b32_e32 v144, 4, v151
	v_cndmask_b32_e64 v146, v194, v146, s[6:7]
	v_lshlrev_b32_e32 v216, 2, v146
	v_xor_b32_e32 v146, 32, v194
	v_cmp_lt_i32_e64 s[6:7], v146, v147
	v_lshl_add_u64 v[128:129], v[128:129], 0, v[144:145]
	flat_load_dwordx4 v[140:143], v[128:129]
	flat_load_dwordx4 v[136:139], v[128:129] offset:64
	s_waitcnt lgkmcnt(0)
	flat_load_dwordx4 v[132:135], v[128:129] offset:128
	s_nop 0
	flat_load_dwordx4 v[128:131], v[128:129] offset:192
	v_cndmask_b32_e64 v146, v194, v146, s[6:7]
	v_lshlrev_b32_e32 v217, 2, v146
	v_lshl_add_u64 v[146:147], s[20:21], 0, v[144:145]
	ds_read_b32 v144, v218
	s_mov_b64 s[2:3], 0x122e0000
	v_lshl_add_u64 v[160:161], v[146:147], 0, s[2:3]
	s_mov_b64 s[2:3], 0x122e1000
	v_lshl_add_u64 v[162:163], v[146:147], 0, s[2:3]
	s_waitcnt lgkmcnt(0)
	v_pk_mul_f32 v[186:187], v[124:125], v[144:145] op_sel_hi:[1,0]
	v_pk_mul_f32 v[178:179], v[116:117], v[144:145] op_sel_hi:[1,0]
	v_mul_f32_e32 v116, v187, v187
	v_pk_mul_f32 v[184:185], v[126:127], v[144:145] op_sel_hi:[1,0]
	v_fmac_f32_e32 v116, v186, v186
	v_fmac_f32_e32 v116, v184, v184
	v_pk_mul_f32 v[182:183], v[120:121], v[144:145] op_sel_hi:[1,0]
	v_fmac_f32_e32 v116, v185, v185
	v_fmac_f32_e32 v116, v182, v182
	v_pk_mul_f32 v[180:181], v[122:123], v[144:145] op_sel_hi:[1,0]
	v_fmac_f32_e32 v116, v183, v183
	v_fmac_f32_e32 v116, v180, v180
	v_pk_mul_f32 v[172:173], v[114:115], v[144:145] op_sel_hi:[1,0]
	v_fmac_f32_e32 v116, v181, v181
	v_pk_mul_f32 v[114:115], v[178:179], v[178:179]
	v_pk_mul_f32 v[176:177], v[118:119], v[144:145] op_sel_hi:[1,0]
	v_add_f32_e32 v114, v114, v116
	v_pk_mul_f32 v[174:175], v[112:113], v[144:145] op_sel_hi:[1,0]
	v_pk_mul_f32 v[112:113], v[176:177], v[176:177]
	v_add_f32_e32 v114, v115, v114
	v_add_f32_e32 v112, v112, v114
	v_add_f32_e32 v116, v113, v112
	v_pk_mul_f32 v[114:115], v[174:175], v[174:175]
	v_pk_mul_f32 v[112:113], v[172:173], v[172:173]
	v_add_f32_e32 v114, v114, v116
	v_add_f32_e32 v114, v115, v114
	v_add_f32_e32 v112, v112, v114
	v_add_f32_e32 v112, v113, v112
	ds_bpermute_b32 v113, v216, v112
	v_and_b32_e32 v144, 0xf80, v158
	v_lshl_add_u64 v[168:169], v[160:161], 0, v[144:145]
	v_lshl_add_u64 v[170:171], v[162:163], 0, v[144:145]
	v_lshlrev_b32_e32 v144, 6, v159
	v_lshl_add_u64 v[164:165], v[160:161], 0, v[144:145]
	v_lshl_add_u64 v[166:167], v[162:163], 0, v[144:145]
	s_waitcnt lgkmcnt(0)
	v_add_f32_e32 v219, v112, v113
	v_add_u32_e32 v221, s98, v168
	ds_read_b128 v[116:119], v221
	v_add_u32_e32 v222, s98, v170
	ds_read_b128 v[124:127], v222
	v_add_u32_e32 v223, s98, v164
	ds_read_b128 v[112:115], v223
	v_add_u32_e32 v224, s98, v166
	ds_read_b128 v[120:123], v224
	ds_bpermute_b32 v220, v217, v219
	v_mov_b32_e32 v155, v145
	v_lshl_add_u64 v[156:157], v[154:155], 1, s[20:21]
	v_ashrrev_i32_e32 v159, 31, v158
	s_and_saveexec_b64 s[2:3], vcc
	s_xor_b64 s[2:3], exec, s[2:3]
	v_lshlrev_b64 v[146:147], 8, v[158:159]
	v_lshl_add_u64 v[146:147], v[156:157], 0, v[146:147]
	s_mov_b64 s[6:7], 0x69dfc00
	v_lshl_add_u64 v[188:189], v[146:147], 0, s[6:7]
	s_or_saveexec_b64 s[2:3], s[2:3]
	v_ashrrev_i32_e32 v155, 31, v154
	v_lshl_add_u64 v[146:147], v[154:155], 1, s[20:21]
	s_mov_b64 s[6:7], 0x59e0000
	v_lshl_add_u64 v[154:155], v[146:147], 0, s[6:7]
	s_xor_b64 exec, exec, s[2:3]
	v_lshlrev_b64 v[146:147], 10, v[158:159]
	v_lshl_add_u64 v[188:189], v[154:155], 0, v[146:147]
	s_or_b64 exec, exec, s[2:3]
	s_waitcnt lgkmcnt(0)
	v_add_f32_e32 v144, v219, v220
	v_fmamk_f32 v144, v144, 0x3c800000, v192
	v_mul_f32_e32 v146, 0x4b800000, v144
	v_cmp_gt_f32_e64 s[6:7], s58, v144
	v_lshlrev_b32_e32 v151, 2, v151
	s_nop 0
	v_cndmask_b32_e64 v144, v144, v146, s[6:7]
	v_rsq_f32_e32 v144, v144
	s_nop 0
	v_mul_f32_e32 v146, 0x45800000, v144
	v_cndmask_b32_e64 v144, v144, v146, s[6:7]
	v_pk_mul_f32 v[148:149], v[186:187], v[144:145] op_sel_hi:[1,0]
	v_pk_mul_f32 v[182:183], v[182:183], v[144:145] op_sel_hi:[1,0]
	v_pk_mul_f32 v[146:147], v[184:185], v[144:145] op_sel_hi:[1,0]
	s_waitcnt vmcnt(0) lgkmcnt(0)
	v_pk_mul_f32 v[148:149], v[140:141], v[148:149]
	v_pk_mul_f32 v[180:181], v[180:181], v[144:145] op_sel_hi:[1,0]
	v_pk_mul_f32 v[182:183], v[136:137], v[182:183]
	v_pk_mul_f32 v[178:179], v[178:179], v[144:145] op_sel_hi:[1,0]
	v_pk_mul_f32 v[174:175], v[174:175], v[144:145] op_sel_hi:[1,0]
	v_pk_mul_f32 v[146:147], v[142:143], v[146:147]
	v_pk_mul_f32 v[180:181], v[138:139], v[180:181]
	v_pk_mul_f32 v[176:177], v[176:177], v[144:145] op_sel_hi:[1,0]
	v_pk_mul_f32 v[178:179], v[132:133], v[178:179]
	v_pk_mul_f32 v[172:173], v[172:173], v[144:145] op_sel_hi:[1,0]
	v_pk_mul_f32 v[174:175], v[128:129], v[174:175]
	v_pk_mul_f32 v[184:185], v[124:125], v[182:183]
	v_pk_mul_f32 v[124:125], v[124:125], v[148:149]
	v_pk_mul_f32 v[176:177], v[134:135], v[176:177]
	v_pk_mul_f32 v[172:173], v[130:131], v[172:173]
	v_pk_mul_f32 v[186:187], v[126:127], v[180:181]
	v_pk_fma_f32 v[184:185], v[116:117], v[148:149], v[184:185] neg_lo:[0,0,1] neg_hi:[0,0,1]
	v_pk_mul_f32 v[126:127], v[126:127], v[146:147]
	v_pk_fma_f32 v[116:117], v[116:117], v[182:183], v[124:125]
	v_pk_mul_f32 v[124:125], v[120:121], v[174:175]
	v_pk_mul_f32 v[120:121], v[120:121], v[178:179]
	v_pk_fma_f32 v[186:187], v[118:119], v[146:147], v[186:187] neg_lo:[0,0,1] neg_hi:[0,0,1]
	v_pk_fma_f32 v[118:119], v[118:119], v[180:181], v[126:127]
	v_pk_mul_f32 v[126:127], v[122:123], v[172:173]
	v_pk_fma_f32 v[124:125], v[112:113], v[178:179], v[124:125] neg_lo:[0,0,1] neg_hi:[0,0,1]
	v_pk_mul_f32 v[122:123], v[122:123], v[176:177]
	v_pk_fma_f32 v[112:113], v[112:113], v[174:175], v[120:121]
	v_lshlrev_b32_e32 v144, 1, v151
	v_pk_fma_f32 v[126:127], v[114:115], v[176:177], v[126:127] neg_lo:[0,0,1] neg_hi:[0,0,1]
	v_pk_fma_f32 v[114:115], v[114:115], v[172:173], v[122:123]
	v_lshl_add_u64 v[122:123], v[188:189], 0, v[144:145]
	v_cvt_pk_bf16_f32 v112, v112, v113
	v_or_b32_e32 v172, 16, v158
	v_cvt_pk_bf16_f32 v113, v114, v115
	global_store_dwordx2 v[122:123], v[112:113], off offset:96
	v_lshlrev_b32_e32 v112, 6, v172
	v_cvt_pk_bf16_f32 v120, v184, v185
	v_cvt_pk_bf16_f32 v121, v186, v187
	v_cvt_pk_bf16_f32 v116, v116, v117
	v_cvt_pk_bf16_f32 v117, v118, v119
	v_and_b32_e32 v112, 0x7c0, v112
	v_mov_b32_e32 v113, v145
	global_store_dwordx2 v[122:123], v[120:121], off
	global_store_dwordx2 v[122:123], v[116:117], off offset:32
	v_cvt_pk_bf16_f32 v116, v124, v125
	v_cvt_pk_bf16_f32 v117, v126, v127
	global_store_dwordx2 v[122:123], v[116:117], off offset:64
	v_lshl_add_u64 v[114:115], v[160:161], 0, v[112:113]
	v_lshl_add_u64 v[120:121], v[162:163], 0, v[112:113]
	v_add_u32_e32 v221, s98, v168
	ds_read_b128 v[116:119], v221
	v_add_u32_e32 v222, s98, v170
	ds_read_b128 v[124:127], v222
	s_nop 0
	v_add_u32_e32 v223, s98, v114
	ds_read_b128 v[112:115], v223
	s_nop 0
	v_add_u32_e32 v224, s98, v120
	ds_read_b128 v[120:123], v224
	ds_read_b32 v146, v218 offset:64
	v_ashrrev_i32_e32 v173, 31, v172
	s_waitcnt lgkmcnt(0)
	v_pk_mul_f32 v[174:175], v[108:109], v[146:147] op_sel_hi:[1,0]
	s_nop 0
	v_mul_f32_e32 v148, v175, v175
	v_pk_mul_f32 v[110:111], v[110:111], v[146:147] op_sel_hi:[1,0]
	v_fmac_f32_e32 v148, v174, v174
	v_fmac_f32_e32 v148, v110, v110
	v_pk_mul_f32 v[108:109], v[104:105], v[146:147] op_sel_hi:[1,0]
	v_fmac_f32_e32 v148, v111, v111
	v_fmac_f32_e32 v148, v108, v108
	v_pk_mul_f32 v[106:107], v[106:107], v[146:147] op_sel_hi:[1,0]
	v_fmac_f32_e32 v148, v109, v109
	v_pk_mul_f32 v[104:105], v[100:101], v[146:147] op_sel_hi:[1,0]
	v_fmac_f32_e32 v148, v106, v106
	v_pk_mul_f32 v[102:103], v[102:103], v[146:147] op_sel_hi:[1,0]
	v_pk_mul_f32 v[98:99], v[98:99], v[146:147] op_sel_hi:[1,0]
	v_pk_mul_f32 v[100:101], v[96:97], v[146:147] op_sel_hi:[1,0]
	v_fmac_f32_e32 v148, v107, v107
	v_pk_mul_f32 v[146:147], v[104:105], v[104:105]
	v_pk_mul_f32 v[96:97], v[102:103], v[102:103]
	v_add_f32_e32 v146, v146, v148
	v_add_f32_e32 v146, v147, v146
	v_add_f32_e32 v96, v96, v146
	v_add_f32_e32 v148, v97, v96
	v_pk_mul_f32 v[146:147], v[100:101], v[100:101]
	v_pk_mul_f32 v[96:97], v[98:99], v[98:99]
	v_add_f32_e32 v146, v146, v148
	v_add_f32_e32 v146, v147, v146
	v_add_f32_e32 v96, v96, v146
	v_add_f32_e32 v96, v97, v96
	ds_bpermute_b32 v97, v216, v96
	s_waitcnt lgkmcnt(0)
	v_add_f32_e32 v151, v96, v97
	ds_bpermute_b32 v159, v217, v151
	s_and_saveexec_b64 s[2:3], vcc
	s_xor_b64 s[2:3], exec, s[2:3]
	v_lshlrev_b64 v[96:97], 8, v[172:173]
	v_lshl_add_u64 v[96:97], v[156:157], 0, v[96:97]
	s_mov_b64 s[6:7], 0x69dfc00
	v_lshl_add_u64 v[96:97], v[96:97], 0, s[6:7]
	s_andn2_saveexec_b64 s[2:3], s[2:3]
	v_lshlrev_b64 v[96:97], 10, v[172:173]
	v_lshl_add_u64 v[96:97], v[154:155], 0, v[96:97]
	s_or_b64 exec, exec, s[2:3]
	s_waitcnt lgkmcnt(0)
	v_add_f32_e32 v146, v151, v159
	v_fmamk_f32 v146, v146, 0x3c800000, v192
	v_mul_f32_e32 v147, 0x4b800000, v146
	v_cmp_gt_f32_e64 s[6:7], s58, v146
	v_lshl_add_u64 v[96:97], v[96:97], 0, v[144:145]
	s_nop 0
	v_cndmask_b32_e64 v146, v146, v147, s[6:7]
	v_rsq_f32_e32 v146, v146
	s_nop 0
	v_mul_f32_e32 v147, 0x45800000, v146
	v_cndmask_b32_e64 v146, v146, v147, s[6:7]
	v_pk_mul_f32 v[148:149], v[174:175], v[146:147] op_sel_hi:[1,0]
	v_pk_mul_f32 v[108:109], v[108:109], v[146:147] op_sel_hi:[1,0]
	v_pk_mul_f32 v[106:107], v[106:107], v[146:147] op_sel_hi:[1,0]
	v_pk_mul_f32 v[110:111], v[110:111], v[146:147] op_sel_hi:[1,0]
	v_pk_mul_f32 v[148:149], v[140:141], v[148:149]
	v_pk_mul_f32 v[106:107], v[138:139], v[106:107]
	v_pk_mul_f32 v[108:109], v[136:137], v[108:109]
	v_pk_mul_f32 v[98:99], v[98:99], v[146:147] op_sel_hi:[1,0]
	v_pk_mul_f32 v[110:111], v[142:143], v[110:111]
	v_pk_mul_f32 v[102:103], v[102:103], v[146:147] op_sel_hi:[1,0]
	v_pk_mul_f32 v[104:105], v[104:105], v[146:147] op_sel_hi:[1,0]
	v_pk_mul_f32 v[100:101], v[100:101], v[146:147] op_sel_hi:[1,0]
	v_pk_mul_f32 v[98:99], v[130:131], v[98:99]
	s_waitcnt lgkmcnt(0)
	v_pk_mul_f32 v[146:147], v[124:125], v[108:109]
	v_pk_mul_f32 v[172:173], v[126:127], v[106:107]
	v_pk_mul_f32 v[124:125], v[124:125], v[148:149]
	v_pk_mul_f32 v[102:103], v[134:135], v[102:103]
	v_pk_mul_f32 v[100:101], v[128:129], v[100:101]
	v_pk_fma_f32 v[172:173], v[118:119], v[110:111], v[172:173] neg_lo:[0,0,1] neg_hi:[0,0,1]
	v_pk_fma_f32 v[146:147], v[116:117], v[148:149], v[146:147] neg_lo:[0,0,1] neg_hi:[0,0,1]
	v_pk_mul_f32 v[110:111], v[126:127], v[110:111]
	v_pk_fma_f32 v[108:109], v[116:117], v[108:109], v[124:125]
	v_pk_mul_f32 v[116:117], v[122:123], v[98:99]
	v_pk_mul_f32 v[104:105], v[132:133], v[104:105]
	v_pk_fma_f32 v[106:107], v[118:119], v[106:107], v[110:111]
	v_pk_mul_f32 v[110:111], v[120:121], v[100:101]
	v_pk_fma_f32 v[116:117], v[114:115], v[102:103], v[116:117] neg_lo:[0,0,1] neg_hi:[0,0,1]
	v_pk_mul_f32 v[102:103], v[122:123], v[102:103]
	v_pk_fma_f32 v[110:111], v[112:113], v[104:105], v[110:111] neg_lo:[0,0,1] neg_hi:[0,0,1]
	v_pk_mul_f32 v[104:105], v[120:121], v[104:105]
	v_pk_fma_f32 v[98:99], v[114:115], v[98:99], v[102:103]
	v_cvt_pk_bf16_f32 v102, v146, v147
	v_cvt_pk_bf16_f32 v103, v172, v173
	v_pk_fma_f32 v[100:101], v[112:113], v[100:101], v[104:105]
	global_store_dwordx2 v[96:97], v[102:103], off
	v_cvt_pk_bf16_f32 v102, v108, v109
	v_cvt_pk_bf16_f32 v103, v106, v107
	v_or_b32_e32 v112, 32, v158
	global_store_dwordx2 v[96:97], v[102:103], off offset:32
	v_cvt_pk_bf16_f32 v102, v110, v111
	v_cvt_pk_bf16_f32 v103, v116, v117
	global_store_dwordx2 v[96:97], v[102:103], off offset:64
	v_cvt_pk_bf16_f32 v100, v100, v101
	v_cvt_pk_bf16_f32 v101, v98, v99
	global_store_dwordx2 v[96:97], v[100:101], off offset:96
	v_lshlrev_b32_e32 v96, 6, v112
	v_and_b32_e32 v96, 0xbc0, v96
	v_mov_b32_e32 v97, v145
	v_lshl_add_u64 v[98:99], v[160:161], 0, v[96:97]
	v_lshl_add_u64 v[104:105], v[162:163], 0, v[96:97]
	v_add_u32_e32 v221, s98, v168
	ds_read_b128 v[100:103], v221
	v_add_u32_e32 v222, s98, v170
	ds_read_b128 v[108:111], v222
	s_nop 0
	v_add_u32_e32 v223, s98, v98
	ds_read_b128 v[96:99], v223
	s_nop 0
	v_add_u32_e32 v224, s98, v104
	ds_read_b128 v[104:107], v224
	ds_read_b32 v116, v218 offset:128
	s_waitcnt lgkmcnt(0)
	v_pk_mul_f32 v[114:115], v[92:93], v[116:117] op_sel_hi:[1,0]
	s_nop 0
	v_mul_f32_e32 v113, v115, v115
	v_pk_mul_f32 v[94:95], v[94:95], v[116:117] op_sel_hi:[1,0]
	v_fmac_f32_e32 v113, v114, v114
	v_fmac_f32_e32 v113, v94, v94
	v_pk_mul_f32 v[92:93], v[88:89], v[116:117] op_sel_hi:[1,0]
	v_fmac_f32_e32 v113, v95, v95
	v_fmac_f32_e32 v113, v92, v92
	v_pk_mul_f32 v[90:91], v[90:91], v[116:117] op_sel_hi:[1,0]
	v_fmac_f32_e32 v113, v93, v93
	v_pk_mul_f32 v[88:89], v[84:85], v[116:117] op_sel_hi:[1,0]
	v_fmac_f32_e32 v113, v90, v90
	v_pk_mul_f32 v[86:87], v[86:87], v[116:117] op_sel_hi:[1,0]
	v_pk_mul_f32 v[82:83], v[82:83], v[116:117] op_sel_hi:[1,0]
	v_pk_mul_f32 v[84:85], v[80:81], v[116:117] op_sel_hi:[1,0]
	v_fmac_f32_e32 v113, v91, v91
	v_pk_mul_f32 v[116:117], v[88:89], v[88:89]
	v_pk_mul_f32 v[80:81], v[86:87], v[86:87]
	v_add_f32_e32 v113, v116, v113
	v_add_f32_e32 v113, v117, v113
	v_add_f32_e32 v80, v80, v113
	v_add_f32_e32 v113, v81, v80
	v_pk_mul_f32 v[116:117], v[84:85], v[84:85]
	v_pk_mul_f32 v[80:81], v[82:83], v[82:83]
	v_add_f32_e32 v113, v116, v113
	v_add_f32_e32 v113, v117, v113
	v_add_f32_e32 v80, v80, v113
	v_add_f32_e32 v80, v81, v80
	ds_bpermute_b32 v81, v216, v80
	v_ashrrev_i32_e32 v113, 31, v112
	s_waitcnt lgkmcnt(0)
	v_add_f32_e32 v116, v80, v81
	ds_bpermute_b32 v117, v217, v116
	s_and_saveexec_b64 s[2:3], vcc
	s_xor_b64 s[2:3], exec, s[2:3]
	v_lshlrev_b64 v[80:81], 8, v[112:113]
	v_lshl_add_u64 v[80:81], v[156:157], 0, v[80:81]
	s_mov_b64 s[6:7], 0x69dfc00
	v_lshl_add_u64 v[80:81], v[80:81], 0, s[6:7]
	s_andn2_saveexec_b64 s[2:3], s[2:3]
	v_lshlrev_b64 v[80:81], 10, v[112:113]
	v_lshl_add_u64 v[80:81], v[154:155], 0, v[80:81]
	s_or_b64 exec, exec, s[2:3]
	s_waitcnt lgkmcnt(0)
	v_add_f32_e32 v112, v116, v117
	v_fmamk_f32 v112, v112, 0x3c800000, v192
	v_mul_f32_e32 v113, 0x4b800000, v112
	v_cmp_gt_f32_e64 s[6:7], s58, v112
	v_lshl_add_u64 v[80:81], v[80:81], 0, v[144:145]
	s_nop 0
	v_cndmask_b32_e64 v112, v112, v113, s[6:7]
	v_rsq_f32_e32 v112, v112
	s_nop 0
	v_mul_f32_e32 v113, 0x45800000, v112
	v_cndmask_b32_e64 v112, v112, v113, s[6:7]
	v_pk_mul_f32 v[114:115], v[114:115], v[112:113] op_sel_hi:[1,0]
	v_pk_mul_f32 v[92:93], v[92:93], v[112:113] op_sel_hi:[1,0]
	v_pk_mul_f32 v[90:91], v[90:91], v[112:113] op_sel_hi:[1,0]
	v_pk_mul_f32 v[94:95], v[94:95], v[112:113] op_sel_hi:[1,0]
	v_pk_mul_f32 v[114:115], v[140:141], v[114:115]
	v_pk_mul_f32 v[90:91], v[138:139], v[90:91]
	v_pk_mul_f32 v[92:93], v[136:137], v[92:93]
	v_pk_mul_f32 v[82:83], v[82:83], v[112:113] op_sel_hi:[1,0]
	v_pk_mul_f32 v[94:95], v[142:143], v[94:95]
	v_pk_mul_f32 v[86:87], v[86:87], v[112:113] op_sel_hi:[1,0]
	v_pk_mul_f32 v[88:89], v[88:89], v[112:113] op_sel_hi:[1,0]
	v_pk_mul_f32 v[84:85], v[84:85], v[112:113] op_sel_hi:[1,0]
	v_pk_mul_f32 v[82:83], v[130:131], v[82:83]
	s_waitcnt lgkmcnt(0)
	v_pk_mul_f32 v[112:113], v[108:109], v[92:93]
	v_pk_mul_f32 v[116:117], v[110:111], v[90:91]
	v_pk_mul_f32 v[108:109], v[108:109], v[114:115]
	v_pk_mul_f32 v[86:87], v[134:135], v[86:87]
	v_pk_mul_f32 v[84:85], v[128:129], v[84:85]
	v_pk_fma_f32 v[116:117], v[102:103], v[94:95], v[116:117] neg_lo:[0,0,1] neg_hi:[0,0,1]
	v_pk_fma_f32 v[112:113], v[100:101], v[114:115], v[112:113] neg_lo:[0,0,1] neg_hi:[0,0,1]
	v_pk_mul_f32 v[94:95], v[110:111], v[94:95]
	v_pk_fma_f32 v[92:93], v[100:101], v[92:93], v[108:109]
	v_pk_mul_f32 v[100:101], v[106:107], v[82:83]
	v_pk_mul_f32 v[88:89], v[132:133], v[88:89]
	v_pk_fma_f32 v[90:91], v[102:103], v[90:91], v[94:95]
	v_pk_mul_f32 v[94:95], v[104:105], v[84:85]
	v_pk_fma_f32 v[100:101], v[98:99], v[86:87], v[100:101] neg_lo:[0,0,1] neg_hi:[0,0,1]
	v_pk_mul_f32 v[86:87], v[106:107], v[86:87]
	v_pk_fma_f32 v[94:95], v[96:97], v[88:89], v[94:95] neg_lo:[0,0,1] neg_hi:[0,0,1]
	v_pk_mul_f32 v[88:89], v[104:105], v[88:89]
	v_pk_fma_f32 v[82:83], v[98:99], v[82:83], v[86:87]
	v_cvt_pk_bf16_f32 v86, v112, v113
	v_cvt_pk_bf16_f32 v87, v116, v117
	v_pk_fma_f32 v[84:85], v[96:97], v[84:85], v[88:89]
	global_store_dwordx2 v[80:81], v[86:87], off
	v_cvt_pk_bf16_f32 v86, v92, v93
	v_cvt_pk_bf16_f32 v87, v90, v91
	v_or_b32_e32 v96, 48, v158
	global_store_dwordx2 v[80:81], v[86:87], off offset:32
	v_cvt_pk_bf16_f32 v86, v94, v95
	v_cvt_pk_bf16_f32 v87, v100, v101
	global_store_dwordx2 v[80:81], v[86:87], off offset:64
	v_cvt_pk_bf16_f32 v84, v84, v85
	v_cvt_pk_bf16_f32 v85, v82, v83
	global_store_dwordx2 v[80:81], v[84:85], off offset:96
	v_lshlrev_b32_e32 v80, 6, v96
	v_and_b32_e32 v80, 0xfc0, v80
	v_mov_b32_e32 v81, v145
	v_lshl_add_u64 v[82:83], v[160:161], 0, v[80:81]
	v_lshl_add_u64 v[88:89], v[162:163], 0, v[80:81]
	v_add_u32_e32 v221, s98, v168
	ds_read_b128 v[84:87], v221
	v_add_u32_e32 v222, s98, v170
	ds_read_b128 v[92:95], v222
	s_nop 0
	v_add_u32_e32 v223, s98, v82
	ds_read_b128 v[80:83], v223
	s_nop 0
	v_add_u32_e32 v224, s98, v88
	ds_read_b128 v[88:91], v224
	ds_read_b32 v100, v218 offset:192
	s_waitcnt lgkmcnt(0)
	v_pk_mul_f32 v[98:99], v[76:77], v[100:101] op_sel_hi:[1,0]
	s_nop 0
	v_mul_f32_e32 v97, v99, v99
	v_pk_mul_f32 v[78:79], v[78:79], v[100:101] op_sel_hi:[1,0]
	v_fmac_f32_e32 v97, v98, v98
	v_fmac_f32_e32 v97, v78, v78
	v_pk_mul_f32 v[76:77], v[72:73], v[100:101] op_sel_hi:[1,0]
	v_fmac_f32_e32 v97, v79, v79
	v_fmac_f32_e32 v97, v76, v76
	v_pk_mul_f32 v[74:75], v[74:75], v[100:101] op_sel_hi:[1,0]
	v_fmac_f32_e32 v97, v77, v77
	v_pk_mul_f32 v[72:73], v[68:69], v[100:101] op_sel_hi:[1,0]
	v_fmac_f32_e32 v97, v74, v74
	v_pk_mul_f32 v[70:71], v[70:71], v[100:101] op_sel_hi:[1,0]
	v_pk_mul_f32 v[66:67], v[66:67], v[100:101] op_sel_hi:[1,0]
	v_pk_mul_f32 v[68:69], v[64:65], v[100:101] op_sel_hi:[1,0]
	v_fmac_f32_e32 v97, v75, v75
	v_pk_mul_f32 v[100:101], v[72:73], v[72:73]
	v_pk_mul_f32 v[64:65], v[70:71], v[70:71]
	v_add_f32_e32 v97, v100, v97
	v_add_f32_e32 v97, v101, v97
	v_add_f32_e32 v64, v64, v97
	v_add_f32_e32 v97, v65, v64
	v_pk_mul_f32 v[100:101], v[68:69], v[68:69]
	v_pk_mul_f32 v[64:65], v[66:67], v[66:67]
	v_add_f32_e32 v97, v100, v97
	v_add_f32_e32 v97, v101, v97
	v_add_f32_e32 v64, v64, v97
	v_add_f32_e32 v64, v65, v64
	ds_bpermute_b32 v65, v216, v64
	v_ashrrev_i32_e32 v97, 31, v96
	s_waitcnt lgkmcnt(0)
	v_add_f32_e32 v100, v64, v65
	ds_bpermute_b32 v101, v217, v100
	s_and_saveexec_b64 s[2:3], vcc
	s_xor_b64 s[2:3], exec, s[2:3]
	v_lshlrev_b64 v[64:65], 8, v[96:97]
	v_lshl_add_u64 v[64:65], v[156:157], 0, v[64:65]
	s_mov_b64 s[6:7], 0x69dfc00
	v_lshl_add_u64 v[64:65], v[64:65], 0, s[6:7]
	s_andn2_saveexec_b64 s[2:3], s[2:3]
	v_lshlrev_b64 v[64:65], 10, v[96:97]
	v_lshl_add_u64 v[64:65], v[154:155], 0, v[64:65]
	s_or_b64 exec, exec, s[2:3]
	s_waitcnt lgkmcnt(0)
	v_add_f32_e32 v96, v100, v101
	v_fmamk_f32 v96, v96, 0x3c800000, v192
	v_mul_f32_e32 v97, 0x4b800000, v96
	v_cmp_gt_f32_e64 s[6:7], s58, v96
	v_lshl_add_u64 v[64:65], v[64:65], 0, v[144:145]
	s_movk_i32 s0, 0xfc0
	v_cndmask_b32_e64 v96, v96, v97, s[6:7]
	v_rsq_f32_e32 v96, v96
	s_nop 0
	v_mul_f32_e32 v97, 0x45800000, v96
	v_cndmask_b32_e64 v96, v96, v97, s[6:7]
	v_pk_mul_f32 v[98:99], v[98:99], v[96:97] op_sel_hi:[1,0]
	v_pk_mul_f32 v[76:77], v[76:77], v[96:97] op_sel_hi:[1,0]
	v_pk_mul_f32 v[74:75], v[74:75], v[96:97] op_sel_hi:[1,0]
	v_pk_mul_f32 v[78:79], v[78:79], v[96:97] op_sel_hi:[1,0]
	v_pk_mul_f32 v[98:99], v[140:141], v[98:99]
	v_pk_mul_f32 v[74:75], v[138:139], v[74:75]
	v_pk_mul_f32 v[76:77], v[136:137], v[76:77]
	v_pk_mul_f32 v[66:67], v[66:67], v[96:97] op_sel_hi:[1,0]
	v_pk_mul_f32 v[78:79], v[142:143], v[78:79]
	v_pk_mul_f32 v[70:71], v[70:71], v[96:97] op_sel_hi:[1,0]
	v_pk_mul_f32 v[72:73], v[72:73], v[96:97] op_sel_hi:[1,0]
	v_pk_mul_f32 v[68:69], v[68:69], v[96:97] op_sel_hi:[1,0]
	v_pk_mul_f32 v[66:67], v[130:131], v[66:67]
	s_waitcnt lgkmcnt(0)
	v_pk_mul_f32 v[96:97], v[92:93], v[76:77]
	v_pk_mul_f32 v[100:101], v[94:95], v[74:75]
	v_pk_mul_f32 v[92:93], v[92:93], v[98:99]
	v_pk_mul_f32 v[70:71], v[134:135], v[70:71]
	v_pk_mul_f32 v[68:69], v[128:129], v[68:69]
	v_pk_fma_f32 v[100:101], v[86:87], v[78:79], v[100:101] neg_lo:[0,0,1] neg_hi:[0,0,1]
	v_pk_fma_f32 v[96:97], v[84:85], v[98:99], v[96:97] neg_lo:[0,0,1] neg_hi:[0,0,1]
	v_pk_mul_f32 v[78:79], v[94:95], v[78:79]
	v_pk_fma_f32 v[76:77], v[84:85], v[76:77], v[92:93]
	v_pk_mul_f32 v[84:85], v[90:91], v[66:67]
	v_pk_mul_f32 v[72:73], v[132:133], v[72:73]
	v_pk_fma_f32 v[74:75], v[86:87], v[74:75], v[78:79]
	v_pk_mul_f32 v[78:79], v[88:89], v[68:69]
	v_pk_fma_f32 v[84:85], v[82:83], v[70:71], v[84:85] neg_lo:[0,0,1] neg_hi:[0,0,1]
	v_pk_mul_f32 v[70:71], v[90:91], v[70:71]
	v_pk_fma_f32 v[78:79], v[80:81], v[72:73], v[78:79] neg_lo:[0,0,1] neg_hi:[0,0,1]
	v_pk_mul_f32 v[72:73], v[88:89], v[72:73]
	v_pk_fma_f32 v[66:67], v[82:83], v[66:67], v[70:71]
	v_cvt_pk_bf16_f32 v70, v96, v97
	v_cvt_pk_bf16_f32 v71, v100, v101
	v_pk_fma_f32 v[68:69], v[80:81], v[68:69], v[72:73]
	global_store_dwordx2 v[64:65], v[70:71], off
	v_cvt_pk_bf16_f32 v70, v76, v77
	v_cvt_pk_bf16_f32 v71, v74, v75
	global_store_dwordx2 v[64:65], v[70:71], off offset:32
	v_cvt_pk_bf16_f32 v70, v78, v79
	v_cvt_pk_bf16_f32 v71, v84, v85
	global_store_dwordx2 v[64:65], v[70:71], off offset:64
	v_cvt_pk_bf16_f32 v68, v68, v69
	v_cvt_pk_bf16_f32 v69, v66, v67
	global_store_dwordx2 v[64:65], v[68:69], off offset:96
	v_bitop3_b32 v64, v158, s0, 64 bitop3:0xc8
	v_mov_b32_e32 v65, v145
	v_lshl_add_u64 v[66:67], v[160:161], 0, v[64:65]
	v_lshl_add_u64 v[64:65], v[162:163], 0, v[64:65]
	v_add_u32_e32 v221, s98, v66
	ds_read_b128 v[72:75], v221
	v_add_u32_e32 v222, s98, v64
	ds_read_b128 v[76:79], v222
	s_nop 0
	v_add_u32_e32 v223, s98, v164
	ds_read_b128 v[64:67], v223
	v_add_u32_e32 v224, s98, v166
	ds_read_b128 v[68:71], v224
	ds_read_b32 v82, v218 offset:256
	s_waitcnt lgkmcnt(0)
	v_pk_mul_f32 v[80:81], v[60:61], v[82:83] op_sel_hi:[1,0]
	s_nop 0
	v_mul_f32_e32 v84, v81, v81
	v_pk_mul_f32 v[62:63], v[62:63], v[82:83] op_sel_hi:[1,0]
	v_fmac_f32_e32 v84, v80, v80
	v_fmac_f32_e32 v84, v62, v62
	v_pk_mul_f32 v[60:61], v[56:57], v[82:83] op_sel_hi:[1,0]
	v_fmac_f32_e32 v84, v63, v63
	v_fmac_f32_e32 v84, v60, v60
	v_pk_mul_f32 v[58:59], v[58:59], v[82:83] op_sel_hi:[1,0]
	v_fmac_f32_e32 v84, v61, v61
	v_pk_mul_f32 v[56:57], v[52:53], v[82:83] op_sel_hi:[1,0]
	v_fmac_f32_e32 v84, v58, v58
	v_pk_mul_f32 v[54:55], v[54:55], v[82:83] op_sel_hi:[1,0]
	v_pk_mul_f32 v[50:51], v[50:51], v[82:83] op_sel_hi:[1,0]
	v_pk_mul_f32 v[52:53], v[48:49], v[82:83] op_sel_hi:[1,0]
	v_fmac_f32_e32 v84, v59, v59
	v_pk_mul_f32 v[82:83], v[56:57], v[56:57]
	v_pk_mul_f32 v[48:49], v[54:55], v[54:55]
	v_add_f32_e32 v82, v82, v84
	v_add_f32_e32 v82, v83, v82
	v_add_f32_e32 v48, v48, v82
	v_add_f32_e32 v84, v49, v48
	v_pk_mul_f32 v[82:83], v[52:53], v[52:53]
	v_pk_mul_f32 v[48:49], v[50:51], v[50:51]
	v_add_f32_e32 v82, v82, v84
	v_add_f32_e32 v82, v83, v82
	v_add_f32_e32 v48, v48, v82
	v_add_f32_e32 v48, v49, v48
	ds_bpermute_b32 v49, v216, v48
	v_or_b32_e32 v82, 64, v158
	v_ashrrev_i32_e32 v83, 31, v82
	s_waitcnt lgkmcnt(0)
	v_add_f32_e32 v84, v48, v49
	ds_bpermute_b32 v85, v217, v84
	s_and_saveexec_b64 s[2:3], vcc
	s_xor_b64 s[2:3], exec, s[2:3]
	v_lshlrev_b64 v[48:49], 8, v[82:83]
	v_lshl_add_u64 v[48:49], v[156:157], 0, v[48:49]
	s_mov_b64 s[6:7], 0x69dfc00
	v_lshl_add_u64 v[48:49], v[48:49], 0, s[6:7]
	s_andn2_saveexec_b64 s[2:3], s[2:3]
	v_lshlrev_b64 v[48:49], 10, v[82:83]
	v_lshl_add_u64 v[48:49], v[154:155], 0, v[48:49]
	s_or_b64 exec, exec, s[2:3]
	s_waitcnt lgkmcnt(0)
	v_add_f32_e32 v82, v84, v85
	v_fmamk_f32 v82, v82, 0x3c800000, v192
	v_mul_f32_e32 v83, 0x4b800000, v82
	v_cmp_gt_f32_e64 s[6:7], s58, v82
	v_lshl_add_u64 v[48:49], v[48:49], 0, v[144:145]
	s_nop 0
	v_cndmask_b32_e64 v82, v82, v83, s[6:7]
	v_rsq_f32_e32 v82, v82
	s_nop 0
	v_mul_f32_e32 v83, 0x45800000, v82
	v_cndmask_b32_e64 v82, v82, v83, s[6:7]
	v_pk_mul_f32 v[80:81], v[80:81], v[82:83] op_sel_hi:[1,0]
	v_pk_mul_f32 v[60:61], v[60:61], v[82:83] op_sel_hi:[1,0]
	v_pk_mul_f32 v[58:59], v[58:59], v[82:83] op_sel_hi:[1,0]
	v_pk_mul_f32 v[62:63], v[62:63], v[82:83] op_sel_hi:[1,0]
	v_pk_mul_f32 v[80:81], v[140:141], v[80:81]
	v_pk_mul_f32 v[58:59], v[138:139], v[58:59]
	v_pk_mul_f32 v[60:61], v[136:137], v[60:61]
	v_pk_mul_f32 v[50:51], v[50:51], v[82:83] op_sel_hi:[1,0]
	v_pk_mul_f32 v[62:63], v[142:143], v[62:63]
	v_pk_mul_f32 v[54:55], v[54:55], v[82:83] op_sel_hi:[1,0]
	v_pk_mul_f32 v[56:57], v[56:57], v[82:83] op_sel_hi:[1,0]
	v_pk_mul_f32 v[52:53], v[52:53], v[82:83] op_sel_hi:[1,0]
	v_pk_mul_f32 v[50:51], v[130:131], v[50:51]
	s_waitcnt lgkmcnt(0)
	v_pk_mul_f32 v[82:83], v[76:77], v[60:61]
	v_pk_mul_f32 v[84:85], v[78:79], v[58:59]
	v_pk_mul_f32 v[76:77], v[76:77], v[80:81]
	v_pk_mul_f32 v[54:55], v[134:135], v[54:55]
	v_pk_mul_f32 v[52:53], v[128:129], v[52:53]
	v_pk_fma_f32 v[84:85], v[74:75], v[62:63], v[84:85] neg_lo:[0,0,1] neg_hi:[0,0,1]
	v_pk_fma_f32 v[82:83], v[72:73], v[80:81], v[82:83] neg_lo:[0,0,1] neg_hi:[0,0,1]
	v_pk_mul_f32 v[62:63], v[78:79], v[62:63]
	v_pk_fma_f32 v[60:61], v[72:73], v[60:61], v[76:77]
	v_pk_mul_f32 v[72:73], v[70:71], v[50:51]
	v_pk_mul_f32 v[56:57], v[132:133], v[56:57]
	v_pk_fma_f32 v[58:59], v[74:75], v[58:59], v[62:63]
	v_pk_mul_f32 v[62:63], v[68:69], v[52:53]
	v_pk_fma_f32 v[72:73], v[66:67], v[54:55], v[72:73] neg_lo:[0,0,1] neg_hi:[0,0,1]
	v_pk_mul_f32 v[54:55], v[70:71], v[54:55]
	v_pk_fma_f32 v[62:63], v[64:65], v[56:57], v[62:63] neg_lo:[0,0,1] neg_hi:[0,0,1]
	v_pk_mul_f32 v[56:57], v[68:69], v[56:57]
	v_pk_fma_f32 v[50:51], v[66:67], v[50:51], v[54:55]
	v_cvt_pk_bf16_f32 v54, v82, v83
	v_cvt_pk_bf16_f32 v55, v84, v85
	v_pk_fma_f32 v[52:53], v[64:65], v[52:53], v[56:57]
	global_store_dwordx2 v[48:49], v[54:55], off
	v_cvt_pk_bf16_f32 v54, v60, v61
	v_cvt_pk_bf16_f32 v55, v58, v59
	global_store_dwordx2 v[48:49], v[54:55], off offset:32
	v_cvt_pk_bf16_f32 v54, v62, v63
	v_cvt_pk_bf16_f32 v55, v72, v73
	global_store_dwordx2 v[48:49], v[54:55], off offset:64
	v_cvt_pk_bf16_f32 v52, v52, v53
	v_cvt_pk_bf16_f32 v53, v50, v51
	global_store_dwordx2 v[48:49], v[52:53], off offset:96
	v_bitop3_b32 v48, v158, s0, v211 bitop3:0xc8
	v_mov_b32_e32 v49, v145
	v_or_b32_e32 v64, 0x50, v158
	v_lshl_add_u64 v[50:51], v[160:161], 0, v[48:49]
	v_lshl_add_u64 v[48:49], v[162:163], 0, v[48:49]
	v_add_u32_e32 v221, s98, v50
	ds_read_b128 v[52:55], v221
	v_add_u32_e32 v222, s98, v48
	ds_read_b128 v[60:63], v222
	v_lshlrev_b32_e32 v48, 6, v64
	v_and_b32_e32 v48, 0x7c0, v48
	v_mov_b32_e32 v49, v145
	v_lshl_add_u64 v[50:51], v[160:161], 0, v[48:49]
	v_lshl_add_u64 v[56:57], v[162:163], 0, v[48:49]
	v_add_u32_e32 v223, s98, v50
	ds_read_b128 v[48:51], v223
	s_nop 0
	v_add_u32_e32 v224, s98, v56
	ds_read_b128 v[56:59], v224
	ds_read_b32 v68, v218 offset:320
	s_waitcnt lgkmcnt(0)
	v_pk_mul_f32 v[66:67], v[44:45], v[68:69] op_sel_hi:[1,0]
	s_nop 0
	v_mul_f32_e32 v65, v67, v67
	v_pk_mul_f32 v[46:47], v[46:47], v[68:69] op_sel_hi:[1,0]
	v_fmac_f32_e32 v65, v66, v66
	v_fmac_f32_e32 v65, v46, v46
	v_pk_mul_f32 v[44:45], v[40:41], v[68:69] op_sel_hi:[1,0]
	v_fmac_f32_e32 v65, v47, v47
	v_fmac_f32_e32 v65, v44, v44
	v_pk_mul_f32 v[42:43], v[42:43], v[68:69] op_sel_hi:[1,0]
	v_fmac_f32_e32 v65, v45, v45
	v_pk_mul_f32 v[40:41], v[36:37], v[68:69] op_sel_hi:[1,0]
	v_fmac_f32_e32 v65, v42, v42
	v_pk_mul_f32 v[38:39], v[38:39], v[68:69] op_sel_hi:[1,0]
	v_pk_mul_f32 v[34:35], v[34:35], v[68:69] op_sel_hi:[1,0]
	v_pk_mul_f32 v[36:37], v[32:33], v[68:69] op_sel_hi:[1,0]
	v_fmac_f32_e32 v65, v43, v43
	v_pk_mul_f32 v[68:69], v[40:41], v[40:41]
	v_pk_mul_f32 v[32:33], v[38:39], v[38:39]
	v_add_f32_e32 v65, v68, v65
	v_add_f32_e32 v65, v69, v65
	v_add_f32_e32 v32, v32, v65
	v_add_f32_e32 v65, v33, v32
	v_pk_mul_f32 v[68:69], v[36:37], v[36:37]
	v_pk_mul_f32 v[32:33], v[34:35], v[34:35]
	v_add_f32_e32 v65, v68, v65
	v_add_f32_e32 v65, v69, v65
	v_add_f32_e32 v32, v32, v65
	v_add_f32_e32 v32, v33, v32
	ds_bpermute_b32 v33, v216, v32
	v_ashrrev_i32_e32 v65, 31, v64
	s_waitcnt lgkmcnt(0)
	v_add_f32_e32 v68, v32, v33
	ds_bpermute_b32 v69, v217, v68
	s_and_saveexec_b64 s[2:3], vcc
	s_xor_b64 s[2:3], exec, s[2:3]
	v_lshlrev_b64 v[32:33], 8, v[64:65]
	v_lshl_add_u64 v[32:33], v[156:157], 0, v[32:33]
	s_mov_b64 s[6:7], 0x69dfc00
	v_lshl_add_u64 v[32:33], v[32:33], 0, s[6:7]
	s_andn2_saveexec_b64 s[2:3], s[2:3]
	v_lshlrev_b64 v[32:33], 10, v[64:65]
	v_lshl_add_u64 v[32:33], v[154:155], 0, v[32:33]
	s_or_b64 exec, exec, s[2:3]
	s_waitcnt lgkmcnt(0)
	v_add_f32_e32 v64, v68, v69
	v_fmamk_f32 v64, v64, 0x3c800000, v192
	v_mul_f32_e32 v65, 0x4b800000, v64
	v_cmp_gt_f32_e64 s[6:7], s58, v64
	v_lshl_add_u64 v[32:33], v[32:33], 0, v[144:145]
	s_nop 0
	v_cndmask_b32_e64 v64, v64, v65, s[6:7]
	v_rsq_f32_e32 v64, v64
	s_nop 0
	v_mul_f32_e32 v65, 0x45800000, v64
	v_cndmask_b32_e64 v64, v64, v65, s[6:7]
	v_pk_mul_f32 v[66:67], v[66:67], v[64:65] op_sel_hi:[1,0]
	v_pk_mul_f32 v[44:45], v[44:45], v[64:65] op_sel_hi:[1,0]
	v_pk_mul_f32 v[42:43], v[42:43], v[64:65] op_sel_hi:[1,0]
	v_pk_mul_f32 v[46:47], v[46:47], v[64:65] op_sel_hi:[1,0]
	v_pk_mul_f32 v[66:67], v[140:141], v[66:67]
	v_pk_mul_f32 v[42:43], v[138:139], v[42:43]
	v_pk_mul_f32 v[44:45], v[136:137], v[44:45]
	v_pk_mul_f32 v[34:35], v[34:35], v[64:65] op_sel_hi:[1,0]
	v_pk_mul_f32 v[46:47], v[142:143], v[46:47]
	v_pk_mul_f32 v[38:39], v[38:39], v[64:65] op_sel_hi:[1,0]
	v_pk_mul_f32 v[40:41], v[40:41], v[64:65] op_sel_hi:[1,0]
	v_pk_mul_f32 v[36:37], v[36:37], v[64:65] op_sel_hi:[1,0]
	v_pk_mul_f32 v[34:35], v[130:131], v[34:35]
	s_waitcnt lgkmcnt(0)
	v_pk_mul_f32 v[64:65], v[60:61], v[44:45]
	v_pk_mul_f32 v[68:69], v[62:63], v[42:43]
	v_pk_mul_f32 v[60:61], v[60:61], v[66:67]
	v_pk_mul_f32 v[38:39], v[134:135], v[38:39]
	v_pk_mul_f32 v[36:37], v[128:129], v[36:37]
	v_pk_fma_f32 v[68:69], v[54:55], v[46:47], v[68:69] neg_lo:[0,0,1] neg_hi:[0,0,1]
	v_pk_fma_f32 v[64:65], v[52:53], v[66:67], v[64:65] neg_lo:[0,0,1] neg_hi:[0,0,1]
	v_pk_mul_f32 v[46:47], v[62:63], v[46:47]
	v_pk_fma_f32 v[44:45], v[52:53], v[44:45], v[60:61]
	v_pk_mul_f32 v[52:53], v[58:59], v[34:35]
	v_pk_mul_f32 v[40:41], v[132:133], v[40:41]
	v_pk_fma_f32 v[42:43], v[54:55], v[42:43], v[46:47]
	v_pk_mul_f32 v[46:47], v[56:57], v[36:37]
	v_pk_fma_f32 v[52:53], v[50:51], v[38:39], v[52:53] neg_lo:[0,0,1] neg_hi:[0,0,1]
	v_pk_mul_f32 v[38:39], v[58:59], v[38:39]
	v_pk_fma_f32 v[46:47], v[48:49], v[40:41], v[46:47] neg_lo:[0,0,1] neg_hi:[0,0,1]
	v_pk_mul_f32 v[40:41], v[56:57], v[40:41]
	v_pk_fma_f32 v[34:35], v[50:51], v[34:35], v[38:39]
	v_cvt_pk_bf16_f32 v38, v64, v65
	v_cvt_pk_bf16_f32 v39, v68, v69
	v_pk_fma_f32 v[36:37], v[48:49], v[36:37], v[40:41]
	global_store_dwordx2 v[32:33], v[38:39], off
	v_cvt_pk_bf16_f32 v38, v44, v45
	v_cvt_pk_bf16_f32 v39, v42, v43
	global_store_dwordx2 v[32:33], v[38:39], off offset:32
	v_cvt_pk_bf16_f32 v38, v46, v47
	v_cvt_pk_bf16_f32 v39, v52, v53
	global_store_dwordx2 v[32:33], v[38:39], off offset:64
	v_cvt_pk_bf16_f32 v36, v36, v37
	v_cvt_pk_bf16_f32 v37, v34, v35
	global_store_dwordx2 v[32:33], v[36:37], off offset:96
	v_bitop3_b32 v32, v158, s0, v212 bitop3:0xc8
	v_mov_b32_e32 v33, v145
	v_or_b32_e32 v48, 0x60, v158
	v_lshl_add_u64 v[34:35], v[160:161], 0, v[32:33]
	v_lshl_add_u64 v[32:33], v[162:163], 0, v[32:33]
	v_add_u32_e32 v221, s98, v34
	ds_read_b128 v[36:39], v221
	v_add_u32_e32 v222, s98, v32
	ds_read_b128 v[44:47], v222
	v_lshlrev_b32_e32 v32, 6, v48
	v_and_b32_e32 v32, 0xbc0, v32
	v_mov_b32_e32 v33, v145
	v_lshl_add_u64 v[34:35], v[160:161], 0, v[32:33]
	v_lshl_add_u64 v[40:41], v[162:163], 0, v[32:33]
	v_add_u32_e32 v223, s98, v34
	ds_read_b128 v[32:35], v223
	s_nop 0
	v_add_u32_e32 v224, s98, v40
	ds_read_b128 v[40:43], v224
	ds_read_b32 v52, v218 offset:384
	s_waitcnt lgkmcnt(0)
	v_pk_mul_f32 v[50:51], v[28:29], v[52:53] op_sel_hi:[1,0]
	s_nop 0
	v_mul_f32_e32 v49, v51, v51
	v_pk_mul_f32 v[30:31], v[30:31], v[52:53] op_sel_hi:[1,0]
	v_fmac_f32_e32 v49, v50, v50
	v_fmac_f32_e32 v49, v30, v30
	v_pk_mul_f32 v[28:29], v[24:25], v[52:53] op_sel_hi:[1,0]
	v_fmac_f32_e32 v49, v31, v31
	v_fmac_f32_e32 v49, v28, v28
	v_pk_mul_f32 v[26:27], v[26:27], v[52:53] op_sel_hi:[1,0]
	v_fmac_f32_e32 v49, v29, v29
	v_pk_mul_f32 v[24:25], v[20:21], v[52:53] op_sel_hi:[1,0]
	v_fmac_f32_e32 v49, v26, v26
	v_pk_mul_f32 v[22:23], v[22:23], v[52:53] op_sel_hi:[1,0]
	v_pk_mul_f32 v[18:19], v[18:19], v[52:53] op_sel_hi:[1,0]
	v_pk_mul_f32 v[20:21], v[16:17], v[52:53] op_sel_hi:[1,0]
	v_fmac_f32_e32 v49, v27, v27
	v_pk_mul_f32 v[52:53], v[24:25], v[24:25]
	v_pk_mul_f32 v[16:17], v[22:23], v[22:23]
	v_add_f32_e32 v49, v52, v49
	v_add_f32_e32 v49, v53, v49
	v_add_f32_e32 v16, v16, v49
	v_add_f32_e32 v49, v17, v16
	v_pk_mul_f32 v[52:53], v[20:21], v[20:21]
	v_pk_mul_f32 v[16:17], v[18:19], v[18:19]
	v_add_f32_e32 v49, v52, v49
	v_add_f32_e32 v49, v53, v49
	v_add_f32_e32 v16, v16, v49
	v_add_f32_e32 v16, v17, v16
	ds_bpermute_b32 v17, v216, v16
	v_ashrrev_i32_e32 v49, 31, v48
	s_waitcnt lgkmcnt(0)
	v_add_f32_e32 v52, v16, v17
	ds_bpermute_b32 v53, v217, v52
	s_and_saveexec_b64 s[2:3], vcc
	s_xor_b64 s[2:3], exec, s[2:3]
	v_lshlrev_b64 v[16:17], 8, v[48:49]
	v_lshl_add_u64 v[16:17], v[156:157], 0, v[16:17]
	s_mov_b64 s[6:7], 0x69dfc00
	v_lshl_add_u64 v[16:17], v[16:17], 0, s[6:7]
	s_andn2_saveexec_b64 s[2:3], s[2:3]
	v_lshlrev_b64 v[16:17], 10, v[48:49]
	v_lshl_add_u64 v[16:17], v[154:155], 0, v[16:17]
	s_or_b64 exec, exec, s[2:3]
	s_waitcnt lgkmcnt(0)
	v_add_f32_e32 v48, v52, v53
	v_fmamk_f32 v48, v48, 0x3c800000, v192
	v_mul_f32_e32 v49, 0x4b800000, v48
	v_cmp_gt_f32_e64 s[6:7], s58, v48
	v_lshl_add_u64 v[16:17], v[16:17], 0, v[144:145]
	s_nop 0
	v_cndmask_b32_e64 v48, v48, v49, s[6:7]
	v_rsq_f32_e32 v48, v48
	s_nop 0
	v_mul_f32_e32 v49, 0x45800000, v48
	v_cndmask_b32_e64 v48, v48, v49, s[6:7]
	v_pk_mul_f32 v[50:51], v[50:51], v[48:49] op_sel_hi:[1,0]
	v_pk_mul_f32 v[28:29], v[28:29], v[48:49] op_sel_hi:[1,0]
	v_pk_mul_f32 v[26:27], v[26:27], v[48:49] op_sel_hi:[1,0]
	v_pk_mul_f32 v[30:31], v[30:31], v[48:49] op_sel_hi:[1,0]
	v_pk_mul_f32 v[50:51], v[140:141], v[50:51]
	v_pk_mul_f32 v[26:27], v[138:139], v[26:27]
	v_pk_mul_f32 v[28:29], v[136:137], v[28:29]
	v_pk_mul_f32 v[18:19], v[18:19], v[48:49] op_sel_hi:[1,0]
	v_pk_mul_f32 v[30:31], v[142:143], v[30:31]
	v_pk_mul_f32 v[22:23], v[22:23], v[48:49] op_sel_hi:[1,0]
	v_pk_mul_f32 v[24:25], v[24:25], v[48:49] op_sel_hi:[1,0]
	v_pk_mul_f32 v[20:21], v[20:21], v[48:49] op_sel_hi:[1,0]
	v_pk_mul_f32 v[18:19], v[130:131], v[18:19]
	s_waitcnt lgkmcnt(0)
	v_pk_mul_f32 v[48:49], v[44:45], v[28:29]
	v_pk_mul_f32 v[52:53], v[46:47], v[26:27]
	v_pk_mul_f32 v[44:45], v[44:45], v[50:51]
	v_pk_mul_f32 v[22:23], v[134:135], v[22:23]
	v_pk_mul_f32 v[20:21], v[128:129], v[20:21]
	v_pk_fma_f32 v[52:53], v[38:39], v[30:31], v[52:53] neg_lo:[0,0,1] neg_hi:[0,0,1]
	v_pk_fma_f32 v[48:49], v[36:37], v[50:51], v[48:49] neg_lo:[0,0,1] neg_hi:[0,0,1]
	v_pk_mul_f32 v[30:31], v[46:47], v[30:31]
	v_pk_fma_f32 v[28:29], v[36:37], v[28:29], v[44:45]
	v_pk_mul_f32 v[36:37], v[42:43], v[18:19]
	v_pk_mul_f32 v[24:25], v[132:133], v[24:25]
	v_pk_fma_f32 v[26:27], v[38:39], v[26:27], v[30:31]
	v_pk_mul_f32 v[30:31], v[40:41], v[20:21]
	v_pk_fma_f32 v[36:37], v[34:35], v[22:23], v[36:37] neg_lo:[0,0,1] neg_hi:[0,0,1]
	v_pk_mul_f32 v[22:23], v[42:43], v[22:23]
	v_pk_fma_f32 v[30:31], v[32:33], v[24:25], v[30:31] neg_lo:[0,0,1] neg_hi:[0,0,1]
	v_pk_mul_f32 v[24:25], v[40:41], v[24:25]
	v_pk_fma_f32 v[18:19], v[34:35], v[18:19], v[22:23]
	v_cvt_pk_bf16_f32 v22, v48, v49
	v_cvt_pk_bf16_f32 v23, v52, v53
	v_pk_fma_f32 v[20:21], v[32:33], v[20:21], v[24:25]
	global_store_dwordx2 v[16:17], v[22:23], off
	v_cvt_pk_bf16_f32 v22, v28, v29
	v_cvt_pk_bf16_f32 v23, v26, v27
	global_store_dwordx2 v[16:17], v[22:23], off offset:32
	v_cvt_pk_bf16_f32 v22, v30, v31
	v_cvt_pk_bf16_f32 v23, v36, v37
	global_store_dwordx2 v[16:17], v[22:23], off offset:64
	v_cvt_pk_bf16_f32 v20, v20, v21
	v_cvt_pk_bf16_f32 v21, v18, v19
	global_store_dwordx2 v[16:17], v[20:21], off offset:96
	v_bitop3_b32 v16, v158, s0, v199 bitop3:0xc8
	v_mov_b32_e32 v17, v145
	v_or_b32_e32 v32, 0x70, v158
	v_lshl_add_u64 v[18:19], v[160:161], 0, v[16:17]
	v_lshl_add_u64 v[16:17], v[162:163], 0, v[16:17]
	v_add_u32_e32 v221, s98, v18
	ds_read_b128 v[20:23], v221
	v_add_u32_e32 v222, s98, v16
	ds_read_b128 v[28:31], v222
	v_lshlrev_b32_e32 v16, 6, v32
	v_and_b32_e32 v16, 0xfc0, v16
	v_mov_b32_e32 v17, v145
	v_lshl_add_u64 v[18:19], v[160:161], 0, v[16:17]
	v_lshl_add_u64 v[24:25], v[162:163], 0, v[16:17]
	v_add_u32_e32 v223, s98, v18
	ds_read_b128 v[16:19], v223
	s_nop 0
	v_add_u32_e32 v224, s98, v24
	ds_read_b128 v[24:27], v224
	ds_read_b32 v42, v218 offset:448
	v_ashrrev_i32_e32 v33, 31, v32
	s_waitcnt lgkmcnt(0)
	v_pk_mul_f32 v[40:41], v[0:1], v[42:43] op_sel_hi:[1,0]
	v_pk_mul_f32 v[36:37], v[4:5], v[42:43] op_sel_hi:[1,0]
	v_pk_mul_f32 v[4:5], v[12:13], v[42:43] op_sel_hi:[1,0]
	v_mul_f32_e32 v12, v41, v41
	v_pk_mul_f32 v[38:39], v[2:3], v[42:43] op_sel_hi:[1,0]
	v_fmac_f32_e32 v12, v40, v40
	v_fmac_f32_e32 v12, v38, v38
	v_fmac_f32_e32 v12, v39, v39
	v_fmac_f32_e32 v12, v36, v36
	v_pk_mul_f32 v[34:35], v[6:7], v[42:43] op_sel_hi:[1,0]
	v_fmac_f32_e32 v12, v37, v37
	v_pk_mul_f32 v[8:9], v[8:9], v[42:43] op_sel_hi:[1,0]
	v_fmac_f32_e32 v12, v34, v34
	v_pk_mul_f32 v[6:7], v[10:11], v[42:43] op_sel_hi:[1,0]
	v_fmac_f32_e32 v12, v35, v35
	v_pk_mul_f32 v[10:11], v[8:9], v[8:9]
	v_pk_mul_f32 v[0:1], v[6:7], v[6:7]
	v_add_f32_e32 v10, v10, v12
	v_add_f32_e32 v10, v11, v10
	v_add_f32_e32 v0, v0, v10
	v_add_f32_e32 v12, v1, v0
	v_pk_mul_f32 v[10:11], v[4:5], v[4:5]
	v_pk_mul_f32 v[2:3], v[14:15], v[42:43] op_sel_hi:[1,0]
	v_add_f32_e32 v10, v10, v12
	v_pk_mul_f32 v[0:1], v[2:3], v[2:3]
	v_add_f32_e32 v10, v11, v10
	v_add_f32_e32 v0, v0, v10
	v_add_f32_e32 v0, v1, v0
	ds_bpermute_b32 v1, v216, v0
	s_waitcnt lgkmcnt(0)
	v_add_f32_e32 v10, v0, v1
	ds_bpermute_b32 v11, v217, v10
	s_and_saveexec_b64 s[2:3], vcc
	s_xor_b64 s[2:3], exec, s[2:3]
	v_lshlrev_b64 v[0:1], 8, v[32:33]
	v_lshl_add_u64 v[0:1], v[156:157], 0, v[0:1]
	s_mov_b64 s[6:7], 0x69dfc00
	v_lshl_add_u64 v[0:1], v[0:1], 0, s[6:7]
	s_andn2_saveexec_b64 s[2:3], s[2:3]
	s_cbranch_execz .LBB0_409
	v_lshlrev_b64 v[0:1], 10, v[32:33]
	v_lshl_add_u64 v[0:1], v[154:155], 0, v[0:1]
	s_branch .LBB0_409

	.amdhsa_kernel _Z4mega6Params
		.amdhsa_group_segment_fixed_size 143424
		.amdhsa_private_segment_fixed_size 0
		.amdhsa_kernarg_size 544
		.amdhsa_user_sgpr_count 2
		.amdhsa_user_sgpr_dispatch_ptr 0
		.amdhsa_user_sgpr_queue_ptr 0
		.amdhsa_user_sgpr_kernarg_segment_ptr 1
		.amdhsa_user_sgpr_dispatch_id 0
		.amdhsa_user_sgpr_kernarg_preload_length 0
		.amdhsa_user_sgpr_kernarg_preload_offset 0
		.amdhsa_user_sgpr_private_segment_size 0
		.amdhsa_uses_dynamic_stack 0
		.amdhsa_enable_private_segment 0
		.amdhsa_system_sgpr_workgroup_id_x 1
		.amdhsa_system_sgpr_workgroup_id_y 0
		.amdhsa_system_sgpr_workgroup_id_z 0
		.amdhsa_system_sgpr_workgroup_info 0
		.amdhsa_system_vgpr_workitem_id 2
		.amdhsa_next_free_vgpr 256
		.amdhsa_next_free_sgpr 100
		.amdhsa_accum_offset 256
		.amdhsa_reserve_vcc 1
		.amdhsa_float_round_mode_32 0
		.amdhsa_float_round_mode_16_64 0
		.amdhsa_float_denorm_mode_32 3
		.amdhsa_float_denorm_mode_16_64 3
		.amdhsa_dx10_clamp 1
		.amdhsa_ieee_mode 1
		.amdhsa_fp16_overflow 0
		.amdhsa_tg_split 0
		.amdhsa_exception_fp_ieee_invalid_op 0
		.amdhsa_exception_fp_denorm_src 0
		.amdhsa_exception_fp_ieee_div_zero 0
		.amdhsa_exception_fp_ieee_overflow 0
		.amdhsa_exception_fp_ieee_underflow 0
		.amdhsa_exception_fp_ieee_inexact 0
		.amdhsa_exception_int_div_zero 0
	.end_amdhsa_kernel

amdhsa.kernels:
  - .agpr_count:     0
    .args:
      - .offset:         0
        .size:           288
        .value_kind:     by_value
      - .offset:         288
        .size:           4
        .value_kind:     hidden_block_count_x
      - .offset:         292
        .size:           4
        .value_kind:     hidden_block_count_y
      - .offset:         296
        .size:           4
        .value_kind:     hidden_block_count_z
      - .offset:         300
        .size:           2
        .value_kind:     hidden_group_size_x
      - .offset:         302
        .size:           2
        .value_kind:     hidden_group_size_y
      - .offset:         304
        .size:           2
        .value_kind:     hidden_group_size_z
      - .offset:         306
        .size:           2
        .value_kind:     hidden_remainder_x
      - .offset:         308
        .size:           2
        .value_kind:     hidden_remainder_y
      - .offset:         310
        .size:           2
        .value_kind:     hidden_remainder_z
      - .offset:         328
        .size:           8
        .value_kind:     hidden_global_offset_x
      - .offset:         336
        .size:           8
        .value_kind:     hidden_global_offset_y
      - .offset:         344
        .size:           8
        .value_kind:     hidden_global_offset_z
      - .offset:         352
        .size:           2
        .value_kind:     hidden_grid_dims
      - .offset:         376
        .size:           8
        .value_kind:     hidden_multigrid_sync_arg
    .group_segment_fixed_size: 143424
    .kernarg_segment_align: 8
    .kernarg_segment_size: 544
    .language:       OpenCL C
    .language_version:
      - 2
      - 0
    .max_flat_workgroup_size: 512
    .name:           _Z4mega6Params
    .private_segment_fixed_size: 0
    .sgpr_count:     106
    .sgpr_spill_count: 109
    .symbol:         _Z4mega6Params.kd
    .uniform_work_group_size: 1
    .uses_dynamic_stack: false
    .vgpr_count:     256
    .vgpr_spill_count: 0
    .wavefront_size: 64
